# t15 + no s_sleep between grid-barrier polls
# baseline (speedup 1.0000x reference)
.LBB0_369:
	flat_load_dword v25, v[0:1] offset:1024 sc1
	flat_load_dword v10, v[0:1] offset:1280 sc1
	flat_load_dword v11, v[0:1] offset:1536 sc1
	flat_load_dword v12, v[0:1] offset:1792 sc1
	flat_load_dword v13, v[0:1] offset:2048 sc1
	flat_load_dword v14, v[0:1] offset:2304 sc1
	flat_load_dword v15, v[0:1] offset:2560 sc1
	flat_load_dword v16, v[0:1] offset:2816 sc1
	flat_load_dword v17, v[0:1] offset:3072 sc1
	flat_load_dword v18, v[0:1] offset:3328 sc1
	flat_load_dword v19, v[0:1] offset:3584 sc1
	flat_load_dword v20, v[0:1] offset:3840 sc1
	flat_load_dword v21, v[2:3] sc1
	flat_load_dword v22, v[4:5] sc1
	flat_load_dword v23, v[6:7] sc1
	flat_load_dword v24, v[8:9] sc1
	s_or_b64 s[8:9], s[8:9], exec
	s_or_b64 s[6:7], s[6:7], exec
	s_waitcnt vmcnt(0) lgkmcnt(0)
	v_add_u32_e32 v26, v10, v25
	v_add_u32_e32 v26, v26, v11
	v_add_u32_e32 v26, v26, v12
	v_add_u32_e32 v26, v26, v13
	v_add_u32_e32 v26, v26, v14
	v_add_u32_e32 v26, v26, v15
	v_add_u32_e32 v26, v26, v16
	v_add_u32_e32 v26, v26, v17
	v_add_u32_e32 v26, v26, v18
	v_add_u32_e32 v26, v26, v19
	v_add_u32_e32 v26, v26, v20
	v_add_u32_e32 v26, v26, v21
	v_add_u32_e32 v26, v26, v22
	v_add_u32_e32 v26, v26, v23
	v_add_u32_e32 v26, v26, v24
	v_cmp_ne_u32_e32 vcc, s20, v26
	s_and_saveexec_b64 s[10:11], vcc
	s_cbranch_execz .LBB0_368
	s_and_b32 s14, s21, 0xff
	s_mov_b64 s[12:13], -1
	s_cmp_eq_u32 s14, 0
	s_mov_b64 s[16:17], -1
	s_mov_b64 s[14:15], -1
	s_nop 0
	s_cbranch_scc1 .LBB0_372
	s_and_saveexec_b64 s[18:19], s[16:17]
	s_cbranch_execz .LBB0_367
	s_branch .LBB0_375

.LBB0_384:
	s_and_b32 s16, s23, 0xff
	s_mov_b64 s[14:15], -1
	s_cmp_lg_u32 s16, 0
	s_mov_b64 s[16:17], -1
	s_nop 0
	s_cbranch_scc1 .LBB0_388
	v_mov_b64_e32 v[2:3], s[38:39]
	flat_load_dword v0, v[2:3] offset:512 sc1
	s_mov_b64 s[16:17], 0
	s_mov_b64 s[18:19], -1
	s_waitcnt vmcnt(0) lgkmcnt(0)
	v_cmp_eq_u32_e32 vcc, 0, v0
	s_and_saveexec_b64 s[20:21], vcc
	s_cmp_lt_u32 s23, 0x100001
	s_cselect_b64 s[16:17], -1, 0
	s_xor_b64 s[18:19], exec, -1
	s_and_b64 s[16:17], s[16:17], exec
	s_or_b64 exec, exec, s[20:21]

.LBB0_398:
	s_and_b32 s14, s23, 0xff
	s_cmp_lg_u32 s14, 0
	s_mov_b64 s[16:17], -1
	s_nop 0
	s_cbranch_scc0 .LBB0_400
	s_mov_b64 s[18:19], -1
	s_and_saveexec_b64 s[20:21], s[16:17]
	s_cbranch_execz .LBB0_397
	s_branch .LBB0_403

.LBB0_467:
	v_mov_b64_e32 v[14:15], s[38:39]
	flat_load_dword v12, v[14:15] offset:1024 sc1
	flat_load_dword v0, v[14:15] offset:1280 sc1
	flat_load_dword v2, v[14:15] offset:1536 sc1
	flat_load_dword v3, v[14:15] offset:1792 sc1
	flat_load_dword v4, v[14:15] offset:2048 sc1
	flat_load_dword v5, v[14:15] offset:2304 sc1
	flat_load_dword v6, v[14:15] offset:2560 sc1
	flat_load_dword v7, v[14:15] offset:2816 sc1
	flat_load_dword v8, v[14:15] offset:3072 sc1
	flat_load_dword v9, v[14:15] offset:3328 sc1
	flat_load_dword v10, v[14:15] offset:3584 sc1
	flat_load_dword v11, v[14:15] offset:3840 sc1
	v_mov_b64_e32 v[14:15], s[4:5]
	flat_load_dword v13, v[14:15] sc1
	v_mov_b64_e32 v[14:15], s[6:7]
	flat_load_dword v14, v[14:15] sc1
	v_mov_b64_e32 v[16:17], s[8:9]
	flat_load_dword v15, v[16:17] sc1
	v_mov_b64_e32 v[16:17], s[10:11]
	flat_load_dword v16, v[16:17] sc1
	s_or_b64 s[18:19], s[18:19], exec
	s_or_b64 s[16:17], s[16:17], exec
	s_waitcnt vmcnt(0) lgkmcnt(0)
	v_add_u32_e32 v17, v0, v12
	v_add_u32_e32 v17, v17, v2
	v_add_u32_e32 v17, v17, v3
	v_add_u32_e32 v17, v17, v4
	v_add_u32_e32 v17, v17, v5
	v_add_u32_e32 v17, v17, v6
	v_add_u32_e32 v17, v17, v7
	v_add_u32_e32 v17, v17, v8
	v_add_u32_e32 v17, v17, v9
	v_add_u32_e32 v17, v17, v10
	v_add_u32_e32 v17, v17, v11
	v_add_u32_e32 v17, v17, v13
	v_add_u32_e32 v17, v17, v14
	v_add_u32_e32 v17, v17, v15
	v_add_u32_e32 v17, v17, v16
	v_cmp_ne_u32_e32 vcc, s30, v17
	s_and_saveexec_b64 s[20:21], vcc
	s_cbranch_execz .LBB0_466
	s_and_b32 s24, s31, 0xff
	s_mov_b64 s[22:23], -1
	s_cmp_eq_u32 s24, 0
	s_mov_b64 s[26:27], -1
	s_mov_b64 s[24:25], -1
	s_nop 0
	s_cbranch_scc1 .LBB0_470
	s_and_saveexec_b64 s[28:29], s[26:27]
	s_cbranch_execz .LBB0_465
	s_branch .LBB0_473

.LBB0_481:
	s_and_b32 s18, s25, 0xff
	s_mov_b64 s[16:17], -1
	s_cmp_lg_u32 s18, 0
	s_mov_b64 s[18:19], -1
	s_nop 0
	s_cbranch_scc1 .LBB0_485
	v_mov_b64_e32 v[4:5], s[38:39]
	flat_load_dword v0, v[4:5] offset:512 sc1
	s_mov_b64 s[18:19], 0
	s_mov_b64 s[20:21], -1
	s_waitcnt vmcnt(0) lgkmcnt(0)
	v_cmp_eq_u32_e32 vcc, 0, v0
	s_and_saveexec_b64 s[22:23], vcc
	s_cmp_lt_u32 s25, 0x100001
	s_cselect_b64 s[18:19], -1, 0
	s_xor_b64 s[20:21], exec, -1
	s_and_b64 s[18:19], s[18:19], exec
	s_or_b64 exec, exec, s[22:23]

.LBB0_495:
	s_and_b32 s18, s25, 0xff
	s_mov_b64 s[16:17], -1
	s_cmp_lg_u32 s18, 0
	s_mov_b64 s[20:21], -1
	s_nop 0
	s_cbranch_scc0 .LBB0_497
	s_and_saveexec_b64 s[22:23], s[20:21]
	s_cbranch_execz .LBB0_494
	s_branch .LBB0_500

.LBB0_593:
	v_mov_b64_e32 v[14:15], s[6:7]
	flat_load_dword v12, v[14:15] offset:1024 sc1
	flat_load_dword v0, v[14:15] offset:1280 sc1
	flat_load_dword v2, v[14:15] offset:1536 sc1
	flat_load_dword v3, v[14:15] offset:1792 sc1
	flat_load_dword v4, v[14:15] offset:2048 sc1
	flat_load_dword v5, v[14:15] offset:2304 sc1
	flat_load_dword v6, v[14:15] offset:2560 sc1
	flat_load_dword v7, v[14:15] offset:2816 sc1
	flat_load_dword v8, v[14:15] offset:3072 sc1
	flat_load_dword v9, v[14:15] offset:3328 sc1
	flat_load_dword v10, v[14:15] offset:3584 sc1
	flat_load_dword v11, v[14:15] offset:3840 sc1
	v_mov_b64_e32 v[14:15], s[8:9]
	flat_load_dword v13, v[14:15] sc1
	v_mov_b64_e32 v[14:15], s[10:11]
	flat_load_dword v14, v[14:15] sc1
	v_mov_b64_e32 v[16:17], s[12:13]
	flat_load_dword v15, v[16:17] sc1
	v_mov_b64_e32 v[16:17], s[14:15]
	flat_load_dword v16, v[16:17] sc1
	s_or_b64 s[22:23], s[22:23], exec
	s_or_b64 s[20:21], s[20:21], exec
	s_waitcnt vmcnt(0) lgkmcnt(0)
	v_add_u32_e32 v17, v0, v12
	v_add_u32_e32 v17, v17, v2
	v_add_u32_e32 v17, v17, v3
	v_add_u32_e32 v17, v17, v4
	v_add_u32_e32 v17, v17, v5
	v_add_u32_e32 v17, v17, v6
	v_add_u32_e32 v17, v17, v7
	v_add_u32_e32 v17, v17, v8
	v_add_u32_e32 v17, v17, v9
	v_add_u32_e32 v17, v17, v10
	v_add_u32_e32 v17, v17, v11
	v_add_u32_e32 v17, v17, v13
	v_add_u32_e32 v17, v17, v14
	v_add_u32_e32 v17, v17, v15
	v_add_u32_e32 v17, v17, v16
	v_cmp_ne_u32_e32 vcc, s36, v17
	s_and_saveexec_b64 s[24:25], vcc
	s_cbranch_execz .LBB0_592
	s_and_b32 s28, s37, 0xff
	s_mov_b64 s[26:27], -1
	s_cmp_eq_u32 s28, 0
	s_mov_b64 s[30:31], -1
	s_mov_b64 s[28:29], -1
	s_nop 0
	s_cbranch_scc1 .LBB0_596
	s_and_saveexec_b64 s[34:35], s[30:31]
	s_cbranch_execz .LBB0_591
	s_branch .LBB0_599

.LBB0_607:
	s_and_b32 s22, s29, 0xff
	s_mov_b64 s[20:21], -1
	s_cmp_lg_u32 s22, 0
	s_mov_b64 s[22:23], -1
	s_nop 0
	s_cbranch_scc1 .LBB0_611
	v_mov_b64_e32 v[4:5], s[6:7]
	flat_load_dword v0, v[4:5] offset:512 sc1
	s_mov_b64 s[22:23], 0
	s_mov_b64 s[24:25], -1
	s_waitcnt vmcnt(0) lgkmcnt(0)
	v_cmp_eq_u32_e32 vcc, 0, v0
	s_and_saveexec_b64 s[26:27], vcc
	s_cmp_lt_u32 s29, 0x100001
	s_cselect_b64 s[22:23], -1, 0
	s_xor_b64 s[24:25], exec, -1
	s_and_b64 s[22:23], s[22:23], exec
	s_or_b64 exec, exec, s[26:27]

.LBB0_621:
	s_and_b32 s22, s29, 0xff
	s_mov_b64 s[20:21], -1
	s_cmp_lg_u32 s22, 0
	s_mov_b64 s[24:25], -1
	s_nop 0
	s_cbranch_scc0 .LBB0_623
	s_and_saveexec_b64 s[26:27], s[24:25]
	s_cbranch_execz .LBB0_620
	s_branch .LBB0_626

.LBB0_1321:
	v_mov_b64_e32 v[14:15], s[6:7]
	flat_load_dword v12, v[14:15] offset:1024 sc1
	flat_load_dword v0, v[14:15] offset:1280 sc1
	flat_load_dword v2, v[14:15] offset:1536 sc1
	flat_load_dword v3, v[14:15] offset:1792 sc1
	flat_load_dword v4, v[14:15] offset:2048 sc1
	flat_load_dword v5, v[14:15] offset:2304 sc1
	flat_load_dword v6, v[14:15] offset:2560 sc1
	flat_load_dword v7, v[14:15] offset:2816 sc1
	flat_load_dword v8, v[14:15] offset:3072 sc1
	flat_load_dword v9, v[14:15] offset:3328 sc1
	flat_load_dword v10, v[14:15] offset:3584 sc1
	flat_load_dword v11, v[14:15] offset:3840 sc1
	v_mov_b64_e32 v[14:15], s[10:11]
	flat_load_dword v13, v[14:15] sc1
	v_mov_b64_e32 v[14:15], s[12:13]
	flat_load_dword v14, v[14:15] sc1
	v_mov_b64_e32 v[16:17], s[14:15]
	flat_load_dword v15, v[16:17] sc1
	v_mov_b64_e32 v[16:17], s[16:17]
	flat_load_dword v16, v[16:17] sc1
	s_or_b64 s[24:25], s[24:25], exec
	s_or_b64 s[22:23], s[22:23], exec
	s_waitcnt vmcnt(0) lgkmcnt(0)
	v_add_u32_e32 v17, v0, v12
	v_add_u32_e32 v17, v17, v2
	v_add_u32_e32 v17, v17, v3
	v_add_u32_e32 v17, v17, v4
	v_add_u32_e32 v17, v17, v5
	v_add_u32_e32 v17, v17, v6
	v_add_u32_e32 v17, v17, v7
	v_add_u32_e32 v17, v17, v8
	v_add_u32_e32 v17, v17, v9
	v_add_u32_e32 v17, v17, v10
	v_add_u32_e32 v17, v17, v11
	v_add_u32_e32 v17, v17, v13
	v_add_u32_e32 v17, v17, v14
	v_add_u32_e32 v17, v17, v15
	v_add_u32_e32 v17, v17, v16
	v_cmp_ne_u32_e32 vcc, s38, v17
	s_and_saveexec_b64 s[26:27], vcc
	s_cbranch_execz .LBB0_1320
	s_and_b32 s30, s39, 0xff
	s_mov_b64 s[28:29], -1
	s_cmp_eq_u32 s30, 0
	s_mov_b64 s[34:35], -1
	s_mov_b64 s[30:31], -1
	s_nop 0
	s_cbranch_scc1 .LBB0_1324
	s_and_saveexec_b64 s[36:37], s[34:35]
	s_cbranch_execz .LBB0_1319
	s_branch .LBB0_1327

.LBB0_1335:
	s_and_b32 s24, s31, 0xff
	s_mov_b64 s[22:23], -1
	s_cmp_lg_u32 s24, 0
	s_mov_b64 s[24:25], -1
	s_nop 0
	s_cbranch_scc1 .LBB0_1339
	v_mov_b64_e32 v[4:5], s[6:7]
	flat_load_dword v0, v[4:5] offset:512 sc1
	s_mov_b64 s[24:25], 0
	s_mov_b64 s[26:27], -1
	s_waitcnt vmcnt(0) lgkmcnt(0)
	v_cmp_eq_u32_e32 vcc, 0, v0
	s_and_saveexec_b64 s[28:29], vcc
	s_cmp_lt_u32 s31, 0x100001
	s_cselect_b64 s[24:25], -1, 0
	s_xor_b64 s[26:27], exec, -1
	s_and_b64 s[24:25], s[24:25], exec
	s_or_b64 exec, exec, s[28:29]

.LBB0_1349:
	s_and_b32 s24, s31, 0xff
	s_mov_b64 s[22:23], -1
	s_cmp_lg_u32 s24, 0
	s_mov_b64 s[26:27], -1
	s_nop 0
	s_cbranch_scc0 .LBB0_1351
	s_and_saveexec_b64 s[28:29], s[26:27]
	s_cbranch_execz .LBB0_1348
	s_branch .LBB0_1354

.LBB0_1732:
	v_mov_b64_e32 v[14:15], s[38:39]
	flat_load_dword v12, v[14:15] offset:1024 sc1
	flat_load_dword v0, v[14:15] offset:1280 sc1
	flat_load_dword v2, v[14:15] offset:1536 sc1
	flat_load_dword v3, v[14:15] offset:1792 sc1
	flat_load_dword v4, v[14:15] offset:2048 sc1
	flat_load_dword v5, v[14:15] offset:2304 sc1
	flat_load_dword v6, v[14:15] offset:2560 sc1
	flat_load_dword v7, v[14:15] offset:2816 sc1
	flat_load_dword v8, v[14:15] offset:3072 sc1
	flat_load_dword v9, v[14:15] offset:3328 sc1
	flat_load_dword v10, v[14:15] offset:3584 sc1
	flat_load_dword v11, v[14:15] offset:3840 sc1
	v_mov_b64_e32 v[14:15], s[4:5]
	flat_load_dword v13, v[14:15] sc1
	v_mov_b64_e32 v[14:15], s[6:7]
	flat_load_dword v14, v[14:15] sc1
	v_mov_b64_e32 v[16:17], s[8:9]
	flat_load_dword v15, v[16:17] sc1
	v_mov_b64_e32 v[16:17], s[10:11]
	flat_load_dword v16, v[16:17] sc1
	s_or_b64 s[20:21], s[20:21], exec
	s_or_b64 s[18:19], s[18:19], exec
	s_waitcnt vmcnt(0) lgkmcnt(0)
	v_add_u32_e32 v17, v0, v12
	v_add_u32_e32 v17, v17, v2
	v_add_u32_e32 v17, v17, v3
	v_add_u32_e32 v17, v17, v4
	v_add_u32_e32 v17, v17, v5
	v_add_u32_e32 v17, v17, v6
	v_add_u32_e32 v17, v17, v7
	v_add_u32_e32 v17, v17, v8
	v_add_u32_e32 v17, v17, v9
	v_add_u32_e32 v17, v17, v10
	v_add_u32_e32 v17, v17, v11
	v_add_u32_e32 v17, v17, v13
	v_add_u32_e32 v17, v17, v14
	v_add_u32_e32 v17, v17, v15
	v_add_u32_e32 v17, v17, v16
	v_cmp_ne_u32_e32 vcc, s34, v17
	s_and_saveexec_b64 s[22:23], vcc
	s_cbranch_execz .LBB0_1731
	s_and_b32 s26, s35, 0xff
	s_mov_b64 s[24:25], -1
	s_cmp_eq_u32 s26, 0
	s_mov_b64 s[28:29], -1
	s_mov_b64 s[26:27], -1
	s_nop 0
	s_cbranch_scc1 .LBB0_1735
	s_and_saveexec_b64 s[30:31], s[28:29]
	s_cbranch_execz .LBB0_1730
	s_branch .LBB0_1738

.LBB0_1746:
	s_and_b32 s20, s27, 0xff
	s_mov_b64 s[18:19], -1
	s_cmp_lg_u32 s20, 0
	s_mov_b64 s[20:21], -1
	s_nop 0
	s_cbranch_scc1 .LBB0_1750
	v_mov_b64_e32 v[4:5], s[38:39]
	flat_load_dword v0, v[4:5] offset:512 sc1
	s_mov_b64 s[20:21], 0
	s_mov_b64 s[22:23], -1
	s_waitcnt vmcnt(0) lgkmcnt(0)
	v_cmp_eq_u32_e32 vcc, 0, v0
	s_and_saveexec_b64 s[24:25], vcc
	s_cmp_lt_u32 s27, 0x100001
	s_cselect_b64 s[20:21], -1, 0
	s_xor_b64 s[22:23], exec, -1
	s_and_b64 s[20:21], s[20:21], exec
	s_or_b64 exec, exec, s[24:25]

.LBB0_1760:
	s_and_b32 s20, s27, 0xff
	s_mov_b64 s[18:19], -1
	s_cmp_lg_u32 s20, 0
	s_mov_b64 s[22:23], -1
	s_nop 0
	s_cbranch_scc0 .LBB0_1762
	s_and_saveexec_b64 s[24:25], s[22:23]
	s_cbranch_execz .LBB0_1759
	s_branch .LBB0_1765
